# attention K staging: QK-norm 8-lane sum via DPP quad_perm/row_half_mirror adds instead of three ds_bpermute LDS round trips per trip (bitwise-identical sums)
# speedup vs baseline: 1.0034x; 1.0034x over previous
; #define LAS __attribute__((address_space(3)))
; __device__ __forceinline__ void attn_phase(LAS unsigned char* lds, const bf16* qkv, bf16* o, const float* qg, const float* kg, const float* sink, int G, int c) {
;     ...
;         v4u qraw[2][4];
; #pragma unroll
;         for (int h = 0; h < 2; ++h) { const bf16* qp = qkv + (size_t)rowof(b, qpos) * QKVN + (head0 + h) * 64 + hh * 8;
; #pragma unroll
;             for (int kk = 0; kk < 4; ++kk) qraw[h][kk] = *(const v4u*)(qp + kk * 16); }
;         __syncthreads();
; #pragma unroll
;         for (int i = 0; i < 7; ++i) {
;             const int part = tid & 7, o = tid >> 3;
;             int slot = -1;
;             if (i < 6) { const int Bc = (meta ? 0 : j - 1) + (i >> 1); if (Bc >= Blo && Bc <= Bhi && (first || Bc == j + 1) && !(meta && i >= 2)) slot = (Bc % 3) * 128 + 64 * (i & 1) + o; }
;             else if (first && o < 32) slot = 384 + o;
;             const v4u kw = kr[i], vw = vr[i];
;             float kf[8] = {bflo(kw.x), bfhi(kw.x), bflo(kw.y), bfhi(kw.y), bflo(kw.z), bfhi(kw.z), bflo(kw.w), bfhi(kw.w)};
;             float ss = 0.f;
; #pragma unroll
;             for (int e = 0; e < 8; ++e) ss += kf[e] * kf[e];
;             ss += __shfl_xor(ss, 1); ss += __shfl_xor(ss, 2); ss += __shfl_xor(ss, 4);
;             const float rs = __builtin_amdgcn_rsqf(ss * (1.0f / 64.0f) + pg8::RMS_EPS);
;             const f32x4 g0 = *(const f32x4*)(kg + part * 8), g1 = *(const f32x4*)(kg + part * 8 + 4);
;             v4u kp; kp.x = pk2(kf[0] * rs * g0.x, kf[1] * rs * g0.y); kp.y = pk2(kf[2] * rs * g0.z, kf[3] * rs * g0.w);
;             kp.z = pk2(kf[4] * rs * g1.x, kf[5] * rs * g1.y); kp.w = pk2(kf[6] * rs * g1.z, kf[7] * rs * g1.w);
;             if (slot >= 0) {
;                 *(LAS v4u*)(lds + K_OFF + slot * KSTR + part * 16) = kp;
;                 LAS unsigned char* vb = lds + V_OFF + (part * 8) * VSTR + slot * 2;
;                 *(LAS unsigned short*)(vb + 0 * VSTR) = (unsigned short)(vw.x & 0xffffu); *(LAS unsigned short*)(vb + 1 * VSTR) = (unsigned short)(vw.x >> 16);
;                 *(LAS unsigned short*)(vb + 2 * VSTR) = (unsigned short)(vw.y & 0xffffu); *(LAS unsigned short*)(vb + 3 * VSTR) = (unsigned short)(vw.y >> 16);
;                 *(LAS unsigned short*)(vb + 4 * VSTR) = (unsigned short)(vw.z & 0xffffu); *(LAS unsigned short*)(vb + 5 * VSTR) = (unsigned short)(vw.z >> 16);
.LBB0_576:
	s_or_b64 exec, exec, s[40:41]
	s_lshl_b32 s4, s84, 7
	s_or_b32 s30, s4, s70
	v_mov_b32_e32 v0, s59
	v_mov_b32_e32 v1, s60
	s_or_b32 s31, s30, 16
	v_cndmask_b32_e64 v0, v0, v1, s[24:25]
	v_add_u32_e32 v1, s31, v153
	v_cndmask_b32_e64 v220, v1, v155, s[24:25]
	v_lshlrev_b32_e32 v0, 1, v0
	v_lshl_add_u32 v92, s85, 2, v0
	v_mov_b32_e32 v0, s6
	v_mov_b32_e32 v1, s7
	v_cmp_gt_i32_e64 s[42:43], 16, v220
	v_or_b32_e32 v93, 1, v92
	s_movk_i32 s4, 0xc00
	v_cndmask_b32_e64 v0, v0, v1, s[42:43]
	v_add_u32_e32 v164, v0, v220
	v_mov_b64_e32 v[0:1], s[62:63]
	v_lshlrev_b32_e32 v166, 6, v92
	v_lshlrev_b32_e32 v162, 6, v93
	v_mad_i64_i32 v[0:1], s[6:7], v164, s4, v[0:1]
	v_ashrrev_i32_e32 v167, 31, v166
	v_ashrrev_i32_e32 v163, 31, v162
	v_lshl_add_u64 v[2:3], v[166:167], 1, v[0:1]
	v_lshlrev_b32_e32 v194, 1, v152
	v_lshl_add_u64 v[0:1], v[162:163], 1, v[0:1]
	v_lshl_add_u64 v[2:3], v[2:3], 0, v[194:195]
	v_lshl_add_u64 v[0:1], v[0:1], 0, v[194:195]
	global_load_dwordx4 v[36:39], v[2:3], off
	global_load_dwordx4 v[32:35], v[2:3], off offset:32
	global_load_dwordx4 v[28:31], v[2:3], off offset:64
	global_load_dwordx4 v[20:23], v[2:3], off offset:96
	global_load_dwordx4 v[12:15], v[0:1], off
	global_load_dwordx4 v[8:11], v[0:1], off offset:32
	global_load_dwordx4 v[4:7], v[0:1], off offset:64
	s_nop 0
	global_load_dwordx4 v[0:3], v[0:1], off offset:96
	v_cmp_ge_i32_e64 s[42:43], v96, v218
	v_cmp_le_i32_e64 s[44:45], v96, v219
	s_and_b64 s[6:7], s[42:43], s[44:45]
	s_and_b64 s[42:43], s[6:7], vcc
	v_mov_b32_e32 v98, -1
	v_mul_lo_u16_e32 v97, 0xab, v96
	s_barrier
	s_and_saveexec_b64 s[40:41], s[42:43]
	v_lshrrev_b16_e32 v88, 9, v97
	v_mul_lo_u16_e32 v88, 3, v88
	v_sub_u16_e32 v88, v96, v88
	v_and_b32_e32 v88, 0xff, v88
	v_lshl_add_u32 v98, v88, 7, v183
	s_or_b64 exec, exec, s[40:41]
	s_waitcnt vmcnt(9)
	v_and_b32_e32 v100, 0xffff0000, v84
	v_lshlrev_b32_e32 v99, 16, v84
	v_mul_f32_e32 v84, v100, v100
	v_lshlrev_b32_e32 v101, 16, v85
	v_fmac_f32_e32 v84, v99, v99
	v_and_b32_e32 v102, 0xffff0000, v85
	v_fmac_f32_e32 v84, v101, v101
	v_lshlrev_b32_e32 v103, 16, v86
	v_fmac_f32_e32 v84, v102, v102
	v_and_b32_e32 v104, 0xffff0000, v86
	v_fmac_f32_e32 v84, v103, v103
	v_lshlrev_b32_e32 v105, 16, v87
	v_fmac_f32_e32 v84, v104, v104
	v_and_b32_e32 v106, 0xffff0000, v87
	v_fmac_f32_e32 v84, v105, v105
	v_fmac_f32_e32 v84, v106, v106
	s_nop 1
	v_add_f32_dpp v84, v84, v84 quad_perm:[1,0,3,2] row_mask:0xf bank_mask:0xf
	v_cmp_lt_i32_e32 vcc, -1, v98
	s_waitcnt lgkmcnt(0)
	s_nop 1
	v_add_f32_dpp v84, v84, v84 quad_perm:[2,3,0,1] row_mask:0xf bank_mask:0xf
	s_waitcnt lgkmcnt(0)
	s_nop 1
	v_add_f32_dpp v84, v84, v84 row_half_mirror row_mask:0xf bank_mask:0xf
	s_waitcnt lgkmcnt(0)
	v_fmamk_f32 v84, v84, 0x3c800000, v193
	v_rsq_f32_e32 v107, v84
	global_load_dwordx4 v[84:87], v[158:159], off offset:16
	global_load_dwordx4 v[88:91], v[158:159], off
	v_mul_f32_e32 v99, v107, v99
	s_waitcnt vmcnt(0)
	v_mul_f32_e32 v88, v88, v99
	v_mul_f32_e32 v99, v107, v100
	v_mul_f32_e32 v89, v89, v99
	v_cvt_pk_bf16_f32 v88, v88, v89
	v_mul_f32_e32 v89, v107, v101
	v_mul_f32_e32 v89, v90, v89
	v_mul_f32_e32 v90, v107, v102
	v_mul_f32_e32 v90, v91, v90
	v_cvt_pk_bf16_f32 v89, v89, v90
	v_mul_f32_e32 v90, v107, v103
	v_mul_f32_e32 v84, v84, v90
	v_mul_f32_e32 v90, v107, v104
	v_mul_f32_e32 v85, v85, v90
	v_cvt_pk_bf16_f32 v90, v84, v85
	v_mul_f32_e32 v84, v107, v105
	v_mul_f32_e32 v85, v107, v106
	v_mul_f32_e32 v84, v86, v84
	v_mul_f32_e32 v85, v87, v85
	v_cvt_pk_bf16_f32 v91, v84, v85
	s_and_saveexec_b64 s[40:41], vcc
	s_cbranch_execz .LBB0_580
	s_movk_i32 s4, 0x90
	v_mad_u64_u32 v[84:85], s[6:7], v98, s4, v[154:155]
	ds_write_b128 v84, v[88:91]
	v_lshl_add_u32 v84, v98, 1, v214
	v_add_u32_e32 v85, 0xea00, v84
	ds_write_b16 v84, v80 offset:59904
	ds_write_b16_d16_hi v84, v80 offset:60744
	ds_write_b16 v84, v81 offset:61584
	ds_write_b16_d16_hi v84, v81 offset:62424
	ds_write_b16 v84, v82 offset:63264
	ds_write_b16_d16_hi v84, v82 offset:64104
	ds_write_b16 v84, v83 offset:64944
	ds_write_b16_d16_hi v85, v83 offset:5880
.LBB0_580:
	s_or_b64 exec, exec, s[40:41]
	v_mov_b32_e32 v84, -1
	s_and_saveexec_b64 s[40:41], s[42:43]
	v_lshrrev_b16_e32 v80, 9, v97
	v_mul_lo_u16_e32 v80, 3, v80
	v_sub_u16_e32 v80, v96, v80
	v_and_b32_e32 v80, 0xff, v80
	v_lshl_add_u32 v84, v80, 7, v213
	s_or_b64 exec, exec, s[40:41]
	v_and_b32_e32 v86, 0xffff0000, v76
	v_lshlrev_b32_e32 v85, 16, v76
	v_mul_f32_e32 v76, v86, v86
	v_lshlrev_b32_e32 v87, 16, v77
	v_fmac_f32_e32 v76, v85, v85
	v_and_b32_e32 v88, 0xffff0000, v77
	v_fmac_f32_e32 v76, v87, v87
	v_lshlrev_b32_e32 v89, 16, v78
	v_fmac_f32_e32 v76, v88, v88
	v_and_b32_e32 v90, 0xffff0000, v78
	v_fmac_f32_e32 v76, v89, v89
	v_lshlrev_b32_e32 v91, 16, v79
	v_fmac_f32_e32 v76, v90, v90
	v_and_b32_e32 v96, 0xffff0000, v79
	v_fmac_f32_e32 v76, v91, v91
	v_fmac_f32_e32 v76, v96, v96
	s_nop 1
	v_add_f32_dpp v76, v76, v76 quad_perm:[1,0,3,2] row_mask:0xf bank_mask:0xf
	v_cmp_lt_i32_e32 vcc, -1, v84
	s_waitcnt lgkmcnt(0)
	s_nop 1
	v_add_f32_dpp v76, v76, v76 quad_perm:[2,3,0,1] row_mask:0xf bank_mask:0xf
	s_waitcnt lgkmcnt(0)
	s_nop 1
	v_add_f32_dpp v76, v76, v76 row_half_mirror row_mask:0xf bank_mask:0xf
	s_waitcnt lgkmcnt(0)
	v_fmamk_f32 v76, v76, 0x3c800000, v193
	v_rsq_f32_e32 v97, v76
	global_load_dwordx4 v[76:79], v[158:159], off offset:16
	global_load_dwordx4 v[80:83], v[158:159], off
	v_mul_f32_e32 v85, v97, v85
	s_waitcnt vmcnt(0)
	v_mul_f32_e32 v80, v80, v85
	v_mul_f32_e32 v85, v97, v86
	v_mul_f32_e32 v81, v81, v85
	v_cvt_pk_bf16_f32 v80, v80, v81
	v_mul_f32_e32 v81, v97, v87
	v_mul_f32_e32 v81, v82, v81
	v_mul_f32_e32 v82, v97, v88
	v_mul_f32_e32 v82, v83, v82
	v_cvt_pk_bf16_f32 v81, v81, v82
	v_mul_f32_e32 v82, v97, v89
	v_mul_f32_e32 v76, v76, v82
	v_mul_f32_e32 v82, v97, v90
	v_mul_f32_e32 v77, v77, v82
	v_cvt_pk_bf16_f32 v82, v76, v77
	v_mul_f32_e32 v76, v97, v91
	v_mul_f32_e32 v77, v97, v96
	v_mul_f32_e32 v76, v78, v76
	v_mul_f32_e32 v77, v79, v77
	v_cvt_pk_bf16_f32 v83, v76, v77
	s_and_saveexec_b64 s[40:41], vcc
	s_cbranch_execz .LBB0_584
	s_movk_i32 s4, 0x90
	v_mad_u64_u32 v[76:77], s[6:7], v84, s4, v[154:155]
	ds_write_b128 v76, v[80:83]
	v_lshl_add_u32 v76, v84, 1, v214
	v_add_u32_e32 v77, 0xea00, v76
	ds_write_b16 v76, v68 offset:59904
	ds_write_b16_d16_hi v76, v68 offset:60744
	ds_write_b16 v76, v69 offset:61584
	ds_write_b16_d16_hi v76, v69 offset:62424
	ds_write_b16 v76, v70 offset:63264
	ds_write_b16_d16_hi v76, v70 offset:64104
	ds_write_b16 v76, v71 offset:64944
	ds_write_b16_d16_hi v77, v71 offset:5880
; #define LAS __attribute__((address_space(3)))
; __device__ __forceinline__ unsigned pk2(float lo, float hi) { return pg8::cvt_pk_bf16(lo, hi); }
; __device__ __forceinline__ void attn_phase(LAS unsigned char* lds, const bf16* qkv, bf16* o, const float* qg, const float* kg, const float* sink, int G, int c) {
;     ...
;         for (int i = 0; i < 7; ++i) {
;             const int part = tid & 7, o = tid >> 3;
;             int slot = -1;
;             if (i < 6) { const int Bc = (meta ? 0 : j - 1) + (i >> 1); if (Bc >= Blo && Bc <= Bhi && (first || Bc == j + 1) && !(meta && i >= 2)) slot = (Bc % 3) * 128 + 64 * (i & 1) + o; }
;             else if (first && o < 32) slot = 384 + o;
;             const v4u kw = kr[i], vw = vr[i];
;             float kf[8] = {bflo(kw.x), bfhi(kw.x), bflo(kw.y), bfhi(kw.y), bflo(kw.z), bfhi(kw.z), bflo(kw.w), bfhi(kw.w)};
;             float ss = 0.f;
; #pragma unroll
;             for (int e = 0; e < 8; ++e) ss += kf[e] * kf[e];
;             ss += __shfl_xor(ss, 1); ss += __shfl_xor(ss, 2); ss += __shfl_xor(ss, 4);
;             const float rs = __builtin_amdgcn_rsqf(ss * (1.0f / 64.0f) + pg8::RMS_EPS);
;             const f32x4 g0 = *(const f32x4*)(kg + part * 8), g1 = *(const f32x4*)(kg + part * 8 + 4);
;             v4u kp; kp.x = pk2(kf[0] * rs * g0.x, kf[1] * rs * g0.y); kp.y = pk2(kf[2] * rs * g0.z, kf[3] * rs * g0.w);
;             kp.z = pk2(kf[4] * rs * g1.x, kf[5] * rs * g1.y); kp.w = pk2(kf[6] * rs * g1.z, kf[7] * rs * g1.w);
;             if (slot >= 0) {
;                 *(LAS v4u*)(lds + K_OFF + slot * KSTR + part * 16) = kp;
;                 LAS unsigned char* vb = lds + V_OFF + (part * 8) * VSTR + slot * 2;
;                 *(LAS unsigned short*)(vb + 0 * VSTR) = (unsigned short)(vw.x & 0xffffu); *(LAS unsigned short*)(vb + 1 * VSTR) = (unsigned short)(vw.x >> 16);
;                 *(LAS unsigned short*)(vb + 2 * VSTR) = (unsigned short)(vw.y & 0xffffu); *(LAS unsigned short*)(vb + 3 * VSTR) = (unsigned short)(vw.y >> 16);
;                 *(LAS unsigned short*)(vb + 4 * VSTR) = (unsigned short)(vw.z & 0xffffu); *(LAS unsigned short*)(vb + 5 * VSTR) = (unsigned short)(vw.z >> 16);
;                 *(LAS unsigned short*)(vb + 6 * VSTR) = (unsigned short)(vw.w & 0xffffu); *(LAS unsigned short*)(vb + 7 * VSTR) = (unsigned short)(vw.w >> 16);
;             }
.LBB0_584:
	s_or_b64 exec, exec, s[40:41]
	s_xor_b64 s[42:43], s[46:47], -1
	v_mov_b32_e32 v77, -1
	v_mul_lo_u16_e32 v76, 0xab, v95
	s_and_saveexec_b64 s[40:41], s[42:43]
	v_lshrrev_b16_e32 v68, 9, v76
	v_mul_lo_u16_e32 v68, 3, v68
	v_sub_u16_e32 v68, v95, v68
	v_and_b32_e32 v68, 0xff, v68
	v_lshl_add_u32 v77, v68, 7, v183
	s_or_b64 exec, exec, s[40:41]
	v_and_b32_e32 v79, 0xffff0000, v72
	v_lshlrev_b32_e32 v78, 16, v72
	v_mul_f32_e32 v68, v79, v79
	v_lshlrev_b32_e32 v80, 16, v73
	v_fmac_f32_e32 v68, v78, v78
	v_and_b32_e32 v81, 0xffff0000, v73
	v_fmac_f32_e32 v68, v80, v80
	v_lshlrev_b32_e32 v82, 16, v74
	v_fmac_f32_e32 v68, v81, v81
	v_and_b32_e32 v83, 0xffff0000, v74
	v_fmac_f32_e32 v68, v82, v82
	v_lshlrev_b32_e32 v84, 16, v75
	v_fmac_f32_e32 v68, v83, v83
	v_and_b32_e32 v85, 0xffff0000, v75
	v_fmac_f32_e32 v68, v84, v84
	v_fmac_f32_e32 v68, v85, v85
	s_nop 1
	v_add_f32_dpp v68, v68, v68 quad_perm:[1,0,3,2] row_mask:0xf bank_mask:0xf
	v_cmp_lt_i32_e32 vcc, -1, v77
	s_waitcnt lgkmcnt(0)
	s_nop 1
	v_add_f32_dpp v68, v68, v68 quad_perm:[2,3,0,1] row_mask:0xf bank_mask:0xf
	s_waitcnt lgkmcnt(0)
	s_nop 1
	v_add_f32_dpp v68, v68, v68 row_half_mirror row_mask:0xf bank_mask:0xf
	s_waitcnt lgkmcnt(0)
	v_fmamk_f32 v68, v68, 0x3c800000, v193
	v_rsq_f32_e32 v86, v68
	global_load_dwordx4 v[68:71], v[158:159], off offset:16
	global_load_dwordx4 v[72:75], v[158:159], off
	v_mul_f32_e32 v78, v86, v78
	s_waitcnt vmcnt(0)
	v_mul_f32_e32 v72, v72, v78
	v_mul_f32_e32 v78, v86, v79
	v_mul_f32_e32 v73, v73, v78
	v_cvt_pk_bf16_f32 v72, v72, v73
	v_mul_f32_e32 v73, v86, v80
	v_mul_f32_e32 v73, v74, v73
	v_mul_f32_e32 v74, v86, v81
	v_mul_f32_e32 v74, v75, v74
	v_cvt_pk_bf16_f32 v73, v73, v74
	v_mul_f32_e32 v74, v86, v82
	v_mul_f32_e32 v68, v68, v74
	v_mul_f32_e32 v74, v86, v83
	v_mul_f32_e32 v69, v69, v74
	v_cvt_pk_bf16_f32 v74, v68, v69
	v_mul_f32_e32 v68, v86, v84
	v_mul_f32_e32 v69, v86, v85
	v_mul_f32_e32 v68, v70, v68
	v_mul_f32_e32 v69, v71, v69
	v_cvt_pk_bf16_f32 v75, v68, v69
	s_and_saveexec_b64 s[40:41], vcc
	s_cbranch_execz .LBB0_588
	s_movk_i32 s4, 0x90
	v_mad_u64_u32 v[68:69], s[6:7], v77, s4, v[154:155]
	ds_write_b128 v68, v[72:75]
	v_lshl_add_u32 v68, v77, 1, v214
	v_add_u32_e32 v69, 0xea00, v68
	ds_write_b16 v68, v64 offset:59904
	ds_write_b16_d16_hi v68, v64 offset:60744
	ds_write_b16 v68, v65 offset:61584
	ds_write_b16_d16_hi v68, v65 offset:62424
	ds_write_b16 v68, v66 offset:63264
	ds_write_b16_d16_hi v68, v66 offset:64104
	ds_write_b16 v68, v67 offset:64944
	ds_write_b16_d16_hi v69, v67 offset:5880
.LBB0_588:
	s_or_b64 exec, exec, s[40:41]
	v_mov_b32_e32 v68, -1
	s_and_saveexec_b64 s[40:41], s[42:43]
	v_lshrrev_b16_e32 v64, 9, v76
	v_mul_lo_u16_e32 v64, 3, v64
	v_sub_u16_e32 v64, v95, v64
	v_and_b32_e32 v64, 0xff, v64
	v_lshl_add_u32 v68, v64, 7, v213
	s_or_b64 exec, exec, s[40:41]
	v_and_b32_e32 v70, 0xffff0000, v60
	v_lshlrev_b32_e32 v69, 16, v60
	v_mul_f32_e32 v60, v70, v70
	v_lshlrev_b32_e32 v71, 16, v61
	v_fmac_f32_e32 v60, v69, v69
	v_and_b32_e32 v72, 0xffff0000, v61
	v_fmac_f32_e32 v60, v71, v71
	v_lshlrev_b32_e32 v73, 16, v62
	v_fmac_f32_e32 v60, v72, v72
	v_and_b32_e32 v74, 0xffff0000, v62
	v_fmac_f32_e32 v60, v73, v73
	v_lshlrev_b32_e32 v75, 16, v63
	v_fmac_f32_e32 v60, v74, v74
	v_and_b32_e32 v76, 0xffff0000, v63
	v_fmac_f32_e32 v60, v75, v75
	v_fmac_f32_e32 v60, v76, v76
	s_nop 1
	v_add_f32_dpp v60, v60, v60 quad_perm:[1,0,3,2] row_mask:0xf bank_mask:0xf
	v_cmp_lt_i32_e32 vcc, -1, v68
	s_waitcnt lgkmcnt(0)
	s_nop 1
	v_add_f32_dpp v60, v60, v60 quad_perm:[2,3,0,1] row_mask:0xf bank_mask:0xf
	s_waitcnt lgkmcnt(0)
	s_nop 1
	v_add_f32_dpp v60, v60, v60 row_half_mirror row_mask:0xf bank_mask:0xf
	s_waitcnt lgkmcnt(0)
	v_fmamk_f32 v60, v60, 0x3c800000, v193
	v_rsq_f32_e32 v77, v60
	global_load_dwordx4 v[60:63], v[158:159], off offset:16
	global_load_dwordx4 v[64:67], v[158:159], off
	v_mul_f32_e32 v69, v77, v69
	s_waitcnt vmcnt(0)
	v_mul_f32_e32 v64, v64, v69
	v_mul_f32_e32 v69, v77, v70
	v_mul_f32_e32 v65, v65, v69
	v_cvt_pk_bf16_f32 v64, v64, v65
	v_mul_f32_e32 v65, v77, v71
	v_mul_f32_e32 v65, v66, v65
	v_mul_f32_e32 v66, v77, v72
	v_mul_f32_e32 v66, v67, v66
	v_cvt_pk_bf16_f32 v65, v65, v66
	v_mul_f32_e32 v66, v77, v73
	v_mul_f32_e32 v60, v60, v66
	v_mul_f32_e32 v66, v77, v74
	v_mul_f32_e32 v61, v61, v66
	v_cvt_pk_bf16_f32 v66, v60, v61
	v_mul_f32_e32 v60, v77, v75
	v_mul_f32_e32 v61, v77, v76
	v_mul_f32_e32 v60, v62, v60
	v_mul_f32_e32 v61, v63, v61
	v_cvt_pk_bf16_f32 v67, v60, v61
	s_and_saveexec_b64 s[40:41], vcc
	s_cbranch_execz .LBB0_592
	s_movk_i32 s4, 0x90
	v_mad_u64_u32 v[60:61], s[6:7], v68, s4, v[154:155]
	ds_write_b128 v60, v[64:67]
	v_lshl_add_u32 v60, v68, 1, v214
	v_add_u32_e32 v61, 0xea00, v60
	ds_write_b16 v60, v52 offset:59904
	ds_write_b16_d16_hi v60, v52 offset:60744
	ds_write_b16 v60, v53 offset:61584
	ds_write_b16_d16_hi v60, v53 offset:62424
	ds_write_b16 v60, v54 offset:63264
	ds_write_b16_d16_hi v60, v54 offset:64104
	ds_write_b16 v60, v55 offset:64944
	ds_write_b16_d16_hi v61, v55 offset:5880
; #define LAS __attribute__((address_space(3)))
; __device__ __forceinline__ unsigned pk2(float lo, float hi) { return pg8::cvt_pk_bf16(lo, hi); }
; __device__ __forceinline__ void attn_phase(LAS unsigned char* lds, const bf16* qkv, bf16* o, const float* qg, const float* kg, const float* sink, int G, int c) {
;     ...
;         for (int i = 0; i < 7; ++i) {
;             const int part = tid & 7, o = tid >> 3;
;             int slot = -1;
;             if (i < 6) { const int Bc = (meta ? 0 : j - 1) + (i >> 1); if (Bc >= Blo && Bc <= Bhi && (first || Bc == j + 1) && !(meta && i >= 2)) slot = (Bc % 3) * 128 + 64 * (i & 1) + o; }
;             else if (first && o < 32) slot = 384 + o;
;             const v4u kw = kr[i], vw = vr[i];
;             float kf[8] = {bflo(kw.x), bfhi(kw.x), bflo(kw.y), bfhi(kw.y), bflo(kw.z), bfhi(kw.z), bflo(kw.w), bfhi(kw.w)};
;             float ss = 0.f;
; #pragma unroll
;             for (int e = 0; e < 8; ++e) ss += kf[e] * kf[e];
;             ss += __shfl_xor(ss, 1); ss += __shfl_xor(ss, 2); ss += __shfl_xor(ss, 4);
;             const float rs = __builtin_amdgcn_rsqf(ss * (1.0f / 64.0f) + pg8::RMS_EPS);
;             const f32x4 g0 = *(const f32x4*)(kg + part * 8), g1 = *(const f32x4*)(kg + part * 8 + 4);
;             v4u kp; kp.x = pk2(kf[0] * rs * g0.x, kf[1] * rs * g0.y); kp.y = pk2(kf[2] * rs * g0.z, kf[3] * rs * g0.w);
;             kp.z = pk2(kf[4] * rs * g1.x, kf[5] * rs * g1.y); kp.w = pk2(kf[6] * rs * g1.z, kf[7] * rs * g1.w);
;             if (slot >= 0) {
;                 *(LAS v4u*)(lds + K_OFF + slot * KSTR + part * 16) = kp;
;                 LAS unsigned char* vb = lds + V_OFF + (part * 8) * VSTR + slot * 2;
;                 *(LAS unsigned short*)(vb + 0 * VSTR) = (unsigned short)(vw.x & 0xffffu); *(LAS unsigned short*)(vb + 1 * VSTR) = (unsigned short)(vw.x >> 16);
;                 *(LAS unsigned short*)(vb + 2 * VSTR) = (unsigned short)(vw.y & 0xffffu); *(LAS unsigned short*)(vb + 3 * VSTR) = (unsigned short)(vw.y >> 16);
;                 *(LAS unsigned short*)(vb + 4 * VSTR) = (unsigned short)(vw.z & 0xffffu); *(LAS unsigned short*)(vb + 5 * VSTR) = (unsigned short)(vw.z >> 16);
;                 *(LAS unsigned short*)(vb + 6 * VSTR) = (unsigned short)(vw.w & 0xffffu); *(LAS unsigned short*)(vb + 7 * VSTR) = (unsigned short)(vw.w >> 16);
;             }
.LBB0_592:
	s_or_b64 exec, exec, s[40:41]
	s_xor_b64 s[10:11], s[10:11], -1
	v_mov_b32_e32 v61, -1
	v_mul_lo_u16_e32 v60, 0xab, v94
	s_and_saveexec_b64 s[40:41], s[10:11]
	v_lshrrev_b16_e32 v52, 9, v60
	v_mul_lo_u16_e32 v52, 3, v52
	v_sub_u16_e32 v52, v94, v52
	v_and_b32_e32 v52, 0xff, v52
	v_lshl_add_u32 v61, v52, 7, v183
	s_or_b64 exec, exec, s[40:41]
	v_and_b32_e32 v63, 0xffff0000, v56
	v_lshlrev_b32_e32 v62, 16, v56
	v_mul_f32_e32 v52, v63, v63
	v_lshlrev_b32_e32 v64, 16, v57
	v_fmac_f32_e32 v52, v62, v62
	v_and_b32_e32 v65, 0xffff0000, v57
	v_fmac_f32_e32 v52, v64, v64
	v_lshlrev_b32_e32 v66, 16, v58
	v_fmac_f32_e32 v52, v65, v65
	v_and_b32_e32 v67, 0xffff0000, v58
	v_fmac_f32_e32 v52, v66, v66
	v_lshlrev_b32_e32 v68, 16, v59
	v_fmac_f32_e32 v52, v67, v67
	v_and_b32_e32 v69, 0xffff0000, v59
	v_fmac_f32_e32 v52, v68, v68
	v_fmac_f32_e32 v52, v69, v69
	s_nop 1
	v_add_f32_dpp v52, v52, v52 quad_perm:[1,0,3,2] row_mask:0xf bank_mask:0xf
	v_cmp_lt_i32_e32 vcc, -1, v61
	s_waitcnt lgkmcnt(0)
	s_nop 1
	v_add_f32_dpp v52, v52, v52 quad_perm:[2,3,0,1] row_mask:0xf bank_mask:0xf
	s_waitcnt lgkmcnt(0)
	s_nop 1
	v_add_f32_dpp v52, v52, v52 row_half_mirror row_mask:0xf bank_mask:0xf
	s_waitcnt lgkmcnt(0)
	v_fmamk_f32 v52, v52, 0x3c800000, v193
	v_rsq_f32_e32 v70, v52
	global_load_dwordx4 v[52:55], v[158:159], off offset:16
	global_load_dwordx4 v[56:59], v[158:159], off
	v_mul_f32_e32 v62, v70, v62
	s_waitcnt vmcnt(0)
	v_mul_f32_e32 v56, v56, v62
	v_mul_f32_e32 v62, v70, v63
	v_mul_f32_e32 v57, v57, v62
	v_cvt_pk_bf16_f32 v56, v56, v57
	v_mul_f32_e32 v57, v70, v64
	v_mul_f32_e32 v57, v58, v57
	v_mul_f32_e32 v58, v70, v65
	v_mul_f32_e32 v58, v59, v58
	v_cvt_pk_bf16_f32 v57, v57, v58
	v_mul_f32_e32 v58, v70, v66
	v_mul_f32_e32 v52, v52, v58
	v_mul_f32_e32 v58, v70, v67
	v_mul_f32_e32 v53, v53, v58
	v_cvt_pk_bf16_f32 v58, v52, v53
	v_mul_f32_e32 v52, v70, v68
	v_mul_f32_e32 v53, v70, v69
	v_mul_f32_e32 v52, v54, v52
	v_mul_f32_e32 v53, v55, v53
	v_cvt_pk_bf16_f32 v59, v52, v53
	s_and_saveexec_b64 s[40:41], vcc
	s_cbranch_execz .LBB0_596
	s_movk_i32 s4, 0x90
	v_mad_u64_u32 v[52:53], s[6:7], v61, s4, v[154:155]
	ds_write_b128 v52, v[56:59]
	v_lshl_add_u32 v52, v61, 1, v214
	v_add_u32_e32 v53, 0xea00, v52
	ds_write_b16 v52, v48 offset:59904
	ds_write_b16_d16_hi v52, v48 offset:60744
	ds_write_b16 v52, v49 offset:61584
	ds_write_b16_d16_hi v52, v49 offset:62424
	ds_write_b16 v52, v50 offset:63264
	ds_write_b16_d16_hi v52, v50 offset:64104
	ds_write_b16 v52, v51 offset:64944
	ds_write_b16_d16_hi v53, v51 offset:5880
; #define LAS __attribute__((address_space(3)))
; __device__ __forceinline__ unsigned pk2(float lo, float hi) { return pg8::cvt_pk_bf16(lo, hi); }
; __device__ __forceinline__ void attn_phase(LAS unsigned char* lds, const bf16* qkv, bf16* o, const float* qg, const float* kg, const float* sink, int G, int c) {
;     ...
;         for (int i = 0; i < 7; ++i) {
;             const int part = tid & 7, o = tid >> 3;
;             int slot = -1;
;             if (i < 6) { const int Bc = (meta ? 0 : j - 1) + (i >> 1); if (Bc >= Blo && Bc <= Bhi && (first || Bc == j + 1) && !(meta && i >= 2)) slot = (Bc % 3) * 128 + 64 * (i & 1) + o; }
;             else if (first && o < 32) slot = 384 + o;
;             const v4u kw = kr[i], vw = vr[i];
;             float kf[8] = {bflo(kw.x), bfhi(kw.x), bflo(kw.y), bfhi(kw.y), bflo(kw.z), bfhi(kw.z), bflo(kw.w), bfhi(kw.w)};
;             float ss = 0.f;
; #pragma unroll
;             for (int e = 0; e < 8; ++e) ss += kf[e] * kf[e];
;             ss += __shfl_xor(ss, 1); ss += __shfl_xor(ss, 2); ss += __shfl_xor(ss, 4);
;             const float rs = __builtin_amdgcn_rsqf(ss * (1.0f / 64.0f) + pg8::RMS_EPS);
;             const f32x4 g0 = *(const f32x4*)(kg + part * 8), g1 = *(const f32x4*)(kg + part * 8 + 4);
;             v4u kp; kp.x = pk2(kf[0] * rs * g0.x, kf[1] * rs * g0.y); kp.y = pk2(kf[2] * rs * g0.z, kf[3] * rs * g0.w);
;             kp.z = pk2(kf[4] * rs * g1.x, kf[5] * rs * g1.y); kp.w = pk2(kf[6] * rs * g1.z, kf[7] * rs * g1.w);
;             if (slot >= 0) {
;                 *(LAS v4u*)(lds + K_OFF + slot * KSTR + part * 16) = kp;
;                 LAS unsigned char* vb = lds + V_OFF + (part * 8) * VSTR + slot * 2;
;                 *(LAS unsigned short*)(vb + 0 * VSTR) = (unsigned short)(vw.x & 0xffffu); *(LAS unsigned short*)(vb + 1 * VSTR) = (unsigned short)(vw.x >> 16);
;                 *(LAS unsigned short*)(vb + 2 * VSTR) = (unsigned short)(vw.y & 0xffffu); *(LAS unsigned short*)(vb + 3 * VSTR) = (unsigned short)(vw.y >> 16);
;                 *(LAS unsigned short*)(vb + 4 * VSTR) = (unsigned short)(vw.z & 0xffffu); *(LAS unsigned short*)(vb + 5 * VSTR) = (unsigned short)(vw.z >> 16);
;                 *(LAS unsigned short*)(vb + 6 * VSTR) = (unsigned short)(vw.w & 0xffffu); *(LAS unsigned short*)(vb + 7 * VSTR) = (unsigned short)(vw.w >> 16);
;             }
.LBB0_596:
	s_or_b64 exec, exec, s[40:41]
	v_mov_b32_e32 v52, -1
	s_and_saveexec_b64 s[40:41], s[10:11]
	v_lshrrev_b16_e32 v48, 9, v60
	v_mul_lo_u16_e32 v48, 3, v48
	v_sub_u16_e32 v48, v94, v48
	v_and_b32_e32 v48, 0xff, v48
	v_lshl_add_u32 v52, v48, 7, v213
	s_or_b64 exec, exec, s[40:41]
	v_and_b32_e32 v54, 0xffff0000, v44
	v_lshlrev_b32_e32 v53, 16, v44
	v_mul_f32_e32 v44, v54, v54
	v_lshlrev_b32_e32 v55, 16, v45
	v_fmac_f32_e32 v44, v53, v53
	v_and_b32_e32 v56, 0xffff0000, v45
	v_fmac_f32_e32 v44, v55, v55
	v_lshlrev_b32_e32 v57, 16, v46
	v_fmac_f32_e32 v44, v56, v56
	v_and_b32_e32 v58, 0xffff0000, v46
	v_fmac_f32_e32 v44, v57, v57
	v_lshlrev_b32_e32 v59, 16, v47
	v_fmac_f32_e32 v44, v58, v58
	v_and_b32_e32 v60, 0xffff0000, v47
	v_fmac_f32_e32 v44, v59, v59
	v_fmac_f32_e32 v44, v60, v60
	s_nop 1
	v_add_f32_dpp v44, v44, v44 quad_perm:[1,0,3,2] row_mask:0xf bank_mask:0xf
	v_cmp_lt_i32_e32 vcc, -1, v52
	s_waitcnt lgkmcnt(0)
	s_nop 1
	v_add_f32_dpp v44, v44, v44 quad_perm:[2,3,0,1] row_mask:0xf bank_mask:0xf
	s_waitcnt lgkmcnt(0)
	s_nop 1
	v_add_f32_dpp v44, v44, v44 row_half_mirror row_mask:0xf bank_mask:0xf
	s_waitcnt lgkmcnt(0)
	v_fmamk_f32 v44, v44, 0x3c800000, v193
	v_rsq_f32_e32 v61, v44
	global_load_dwordx4 v[44:47], v[158:159], off offset:16
	global_load_dwordx4 v[48:51], v[158:159], off
	v_mul_f32_e32 v53, v61, v53
	s_waitcnt vmcnt(0)
	v_mul_f32_e32 v48, v48, v53
	v_mul_f32_e32 v53, v61, v54
	v_mul_f32_e32 v49, v49, v53
	v_cvt_pk_bf16_f32 v48, v48, v49
	v_mul_f32_e32 v49, v61, v55
	v_mul_f32_e32 v49, v50, v49
	v_mul_f32_e32 v50, v61, v56
	v_mul_f32_e32 v50, v51, v50
	v_cvt_pk_bf16_f32 v49, v49, v50
	v_mul_f32_e32 v50, v61, v57
	v_mul_f32_e32 v44, v44, v50
	v_mul_f32_e32 v50, v61, v58
	v_mul_f32_e32 v45, v45, v50
	v_cvt_pk_bf16_f32 v50, v44, v45
	v_mul_f32_e32 v44, v61, v59
	v_mul_f32_e32 v45, v61, v60
	v_mul_f32_e32 v44, v46, v44
	v_mul_f32_e32 v45, v47, v45
	v_cvt_pk_bf16_f32 v51, v44, v45
	s_and_saveexec_b64 s[10:11], vcc
	s_cbranch_execz .LBB0_600
	s_movk_i32 s4, 0x90
	v_mad_u64_u32 v[44:45], s[6:7], v52, s4, v[154:155]
	ds_write_b128 v44, v[48:51]
	v_lshl_add_u32 v44, v52, 1, v214
	v_add_u32_e32 v45, 0xea00, v44
	ds_write_b16 v44, v24 offset:59904
	ds_write_b16_d16_hi v44, v24 offset:60744
	ds_write_b16 v44, v25 offset:61584
	ds_write_b16_d16_hi v44, v25 offset:62424
	ds_write_b16 v44, v26 offset:63264
	ds_write_b16_d16_hi v44, v26 offset:64104
	ds_write_b16 v44, v27 offset:64944
	ds_write_b16_d16_hi v45, v27 offset:5880
.LBB0_600:
	s_or_b64 exec, exec, s[10:11]
	global_load_dwordx4 v[24:27], v[158:159], off
	global_load_dwordx4 v[44:47], v[158:159], off offset:16
	v_and_b32_e32 v49, 0xffff0000, v40
	v_lshlrev_b32_e32 v48, 16, v40
	v_mul_f32_e32 v40, v49, v49
	v_lshlrev_b32_e32 v50, 16, v41
	v_fmac_f32_e32 v40, v48, v48
	v_and_b32_e32 v41, 0xffff0000, v41
	v_fmac_f32_e32 v40, v50, v50
	v_lshlrev_b32_e32 v51, 16, v42
	v_fmac_f32_e32 v40, v41, v41
	v_and_b32_e32 v42, 0xffff0000, v42
	v_fmac_f32_e32 v40, v51, v51
	v_lshlrev_b32_e32 v52, 16, v43
	v_fmac_f32_e32 v40, v42, v42
	v_and_b32_e32 v43, 0xffff0000, v43
	v_fmac_f32_e32 v40, v52, v52
	v_fmac_f32_e32 v40, v43, v43
	s_nop 1
	v_add_f32_dpp v40, v40, v40 quad_perm:[1,0,3,2] row_mask:0xf bank_mask:0xf
	s_and_b64 vcc, s[74:75], s[96:97]
	s_waitcnt lgkmcnt(0)
	s_nop 1
	v_add_f32_dpp v40, v40, v40 quad_perm:[2,3,0,1] row_mask:0xf bank_mask:0xf
	s_waitcnt lgkmcnt(0)
	s_nop 1
	v_add_f32_dpp v40, v40, v40 row_half_mirror row_mask:0xf bank_mask:0xf
	s_waitcnt lgkmcnt(0)
	v_fmamk_f32 v40, v40, 0x3c800000, v193
	v_rsq_f32_e32 v53, v40
	v_add_u32_e32 v40, 0x180, v183
	v_cndmask_b32_e32 v40, -1, v40, vcc
	v_cmp_lt_i32_e32 vcc, -1, v40
	v_mul_f32_e32 v48, v53, v48
	v_mul_f32_e32 v49, v53, v49
	v_mul_f32_e32 v50, v53, v50
	v_mul_f32_e32 v41, v53, v41
	v_mul_f32_e32 v51, v53, v51
	v_mul_f32_e32 v42, v53, v42
	v_mul_f32_e32 v52, v53, v52
	v_mul_f32_e32 v43, v53, v43
	s_waitcnt vmcnt(1)
	v_mul_f32_e32 v24, v24, v48
	v_mul_f32_e32 v25, v25, v49
	v_mul_f32_e32 v26, v26, v50
	v_mul_f32_e32 v27, v27, v41
	s_waitcnt vmcnt(0)
	v_mul_f32_e32 v41, v44, v51
	v_mul_f32_e32 v42, v45, v42
	v_mul_f32_e32 v44, v46, v52
	v_mul_f32_e32 v43, v47, v43
	v_cvt_pk_bf16_f32 v24, v24, v25
	v_cvt_pk_bf16_f32 v25, v26, v27
	v_cvt_pk_bf16_f32 v26, v41, v42
	v_cvt_pk_bf16_f32 v27, v44, v43
	s_and_saveexec_b64 s[10:11], vcc
	s_cbranch_execz .LBB0_602
	s_movk_i32 s4, 0x90
	v_mad_u64_u32 v[42:43], s[6:7], v40, s4, v[154:155]
	ds_write_b128 v42, v[24:27]
	v_lshl_add_u32 v24, v40, 1, v214
	v_add_u32_e32 v25, 0xea00, v24
	ds_write_b16 v24, v16 offset:59904
	ds_write_b16_d16_hi v24, v16 offset:60744
	ds_write_b16 v24, v17 offset:61584
	ds_write_b16_d16_hi v24, v17 offset:62424
	ds_write_b16 v24, v18 offset:63264
	ds_write_b16_d16_hi v24, v18 offset:64104
	ds_write_b16 v24, v19 offset:64944
	ds_write_b16_d16_hi v25, v19 offset:5880
